# v2 + GEMM prologue de-serialisation: tile-1 LDS-DMA loads issued before the first wait (vmcnt 2->8)
# speedup vs baseline: 1.0275x; 1.0029x over previous
; #define PG8_STAGE(bufoff, gbase, voff) do { _Pragma("unroll") for (int _i = 0; _i < 2; ++_i) \
;         __builtin_amdgcn_global_load_lds((const unsigned*)((const char*)(gbase) + (voff)[_i]), (PG8_LAS unsigned*)(lds + (bufoff) + ldsw + _i * 8192), 16, 0, 0); } while (0)
; #define PG8_WAIT_V(n) asm volatile("s_waitcnt vmcnt(" #n ")" ::: "memory")
; #define PG8_BAR __builtin_amdgcn_s_barrier()
; template <class Epi, class Sched, bool ALIGN_EPI = false, bool SP2 = false>
; __device__ __forceinline__ void gemm_phase(PG8_LAS unsigned char* lds, const Gemm g, const Sched& S, const Epi& E) {
;     ...
;         PG8_STAGE(PG8_SB(0, 0), cB, voffB); PG8_STAGE(PG8_SB(0, 1), cB + hstep, voffB); PG8_STAGE(PG8_SA(0, 0), cA, voffA); PG8_STAGE(PG8_SA(0, 1), cA + hstep, voffA);
;         if (wr == 1) PG8_BAR;
;         PG8_WAIT_V(2); PG8_BAR;
;         PG8_STAGE(PG8_SB(1, 0), cB + kstep, voffB); PG8_STAGE(PG8_SA(1, 0), cA + kstep, voffA); PG8_STAGE(PG8_SB(1, 1), cB + hstep + kstep, voffB);
;         PG8_WAIT_V(6); PG8_BAR;
.LBB0_168:
	s_lshl_b32 s6, s6, 5
	s_and_b32 s22, s6, 0x60
	s_mov_b64 s[6:7], 0x80
	s_add_i32 m0, s11, 0x18000
	v_lshl_add_u64 v[6:7], v[6:7], 0, s[6:7]
	s_lshl_b32 s17, s1, 13
	s_lshl_b32 s23, s22, 7
	global_load_lds_dwordx4 v[6:7], off
	v_lshl_add_u64 v[4:5], v[4:5], 0, s[6:7]
	s_add_i32 m0, s11, 0x1a000
	s_add_i32 s38, s11, 0x8000
	s_add_i32 s39, s11, 0xa000
	global_load_lds_dwordx4 v[4:5], off
	v_lshl_add_u64 v[0:1], v[0:1], 0, s[6:7]
	s_mov_b32 m0, s38
	s_add_u32 s20, s30, 0x40080
	global_load_lds_dwordx4 v[0:1], off
	v_lshl_add_u64 v[0:1], v[2:3], 0, s[6:7]
	s_mov_b32 m0, s39
	s_addc_u32 s21, s31, 0
	global_load_lds_dwordx4 v[0:1], off
	s_add_i32 m0, s11, 0x1c000
	v_lshl_add_u64 v[0:1], s[20:21], 0, v[130:131]
	global_load_lds_dwordx4 v[0:1], off
	v_lshl_add_u64 v[0:1], s[20:21], 0, v[134:135]
	s_add_i32 m0, s11, 0x1e000
	v_lshlrev_b32_e32 v2, 2, v144
	global_load_lds_dwordx4 v[0:1], off
	v_lshlrev_b32_e32 v0, 1, v11
	v_lshl_or_b32 v1, v144, 6, v0
	v_and_b32_e32 v2, 32, v2
	s_sext_i32_i16 s46, s0
	v_bitop3_b32 v1, v1, s17, v2 bitop3:0xde
	v_lshlrev_b32_e32 v2, 6, v162
	s_movk_i32 s0, 0x3c0
	v_and_or_b32 v0, v2, s0, v0
	v_lshlrev_b32_e32 v2, 2, v162
	v_and_b32_e32 v2, 32, v2
	v_bitop3_b32 v146, s23, v0, v2 bitop3:0xf6
	v_lshlrev_b32_e32 v0, 8, v162
	v_and_b32_e32 v0, 0x38000, v0
	v_lshlrev_b32_e32 v2, 11, v10
	v_or3_b32 v0, v8, v0, v2
	v_add_u32_e32 v136, v0, v9
	v_lshlrev_b32_e32 v0, 4, v12
	s_waitcnt vmcnt(8)
	s_barrier
	s_waitcnt vmcnt(6)
	s_cmpk_lt_u32 s16, 0x100
	v_and_b32_e32 v0, 0x78000, v0
	s_cselect_b64 s[16:17], -1, 0
	v_or3_b32 v0, v8, v0, v2
	s_add_i32 s41, 0, 0x10000
	s_add_i32 s43, 0, 0x14000
	v_lshl_or_b32 v145, s1, 6, v144
	s_ashr_i32 s40, s42, 31
	v_or_b32_e32 v147, s22, v11
	v_mov_b32_e32 v137, v131
	v_add_u32_e32 v138, v0, v9
	v_mov_b32_e32 v139, v131
	v_mov_b64_e32 v[140:141], 0x800
	v_mov_b64_e32 v[142:143], 0x7ff
	v_add_u32_e32 v148, s41, v146
	v_add_u32_e32 v149, s43, v146
	v_add_u32_e32 v150, 0, v1
	s_barrier
	s_branch .LBB0_171

; #define PG8_STAGE(bufoff, gbase, voff) do { _Pragma("unroll") for (int _i = 0; _i < 2; ++_i) \
;         __builtin_amdgcn_global_load_lds((const unsigned*)((const char*)(gbase) + (voff)[_i]), (PG8_LAS unsigned*)(lds + (bufoff) + ldsw + _i * 8192), 16, 0, 0); } while (0)
; #define PG8_WAIT_V(n) asm volatile("s_waitcnt vmcnt(" #n ")" ::: "memory")
; #define PG8_BAR __builtin_amdgcn_s_barrier()
; template <class Epi, class Sched, bool ALIGN_EPI = false, bool SP2 = false>
; __device__ __forceinline__ void gemm_phase(PG8_LAS unsigned char* lds, const Gemm g, const Sched& S, const Epi& E) {
;     ...
;         PG8_STAGE(PG8_SB(0, 0), cB, voffB); PG8_STAGE(PG8_SB(0, 1), cB + hstep, voffB); PG8_STAGE(PG8_SA(0, 0), cA, voffA); PG8_STAGE(PG8_SA(0, 1), cA + hstep, voffA);
;         if (wr == 1) PG8_BAR;
;         PG8_WAIT_V(2); PG8_BAR;
;         PG8_STAGE(PG8_SB(1, 0), cB + kstep, voffB); PG8_STAGE(PG8_SA(1, 0), cA + kstep, voffA); PG8_STAGE(PG8_SB(1, 1), cB + hstep + kstep, voffB);
;         PG8_WAIT_V(6); PG8_BAR;
.LBB0_593:
	s_add_u32 s14, s94, 0xd403000
	s_addc_u32 s15, s95, 0
	s_lshl_b32 s16, s16, 5
	s_and_b32 s22, s16, 0x60
	s_mov_b64 s[16:17], 0x80
	s_add_i32 m0, s11, 0x18000
	v_lshl_add_u64 v[6:7], v[6:7], 0, s[16:17]
	s_lshl_b32 s19, s18, 13
	s_lshl_b32 s23, s22, 7
	global_load_lds_dwordx4 v[6:7], off
	v_lshl_add_u64 v[4:5], v[4:5], 0, s[16:17]
	s_add_i32 m0, s11, 0x1a000
	s_add_i32 s40, s11, 0x8000
	s_add_i32 s41, s11, 0xa000
	global_load_lds_dwordx4 v[4:5], off
	v_lshl_add_u64 v[0:1], v[0:1], 0, s[16:17]
	s_mov_b32 m0, s40
	s_add_u32 s20, s34, 0x40080
	global_load_lds_dwordx4 v[0:1], off
	v_lshl_add_u64 v[0:1], v[2:3], 0, s[16:17]
	s_mov_b32 m0, s41
	s_addc_u32 s21, s35, 0
	global_load_lds_dwordx4 v[0:1], off
	s_add_i32 m0, s11, 0x1c000
	v_lshl_add_u64 v[0:1], s[20:21], 0, v[130:131]
	global_load_lds_dwordx4 v[0:1], off
	v_lshl_add_u64 v[0:1], s[20:21], 0, v[134:135]
	s_add_i32 m0, s11, 0x1e000
	s_sext_i32_i8 s48, s4
	global_load_lds_dwordx4 v[0:1], off
	v_and_b32_e32 v0, 15, v162
	v_lshlrev_b32_e32 v1, 1, v11
	v_lshlrev_b32_e32 v2, 2, v162
	v_lshlrev_b32_e32 v3, 6, v162
	s_movk_i32 s4, 0x3c0
	v_lshl_or_b32 v148, s18, 6, v0
	v_lshl_or_b32 v0, v0, 6, v1
	v_and_b32_e32 v2, 32, v2
	v_and_or_b32 v1, v3, s4, v1
	v_bitop3_b32 v149, s23, v1, v2 bitop3:0xf6
	v_lshlrev_b32_e32 v1, 8, v162
	v_bitop3_b32 v0, v0, s19, v2 bitop3:0xde
	v_and_b32_e32 v1, 0x38000, v1
	v_lshlrev_b32_e32 v2, 11, v10
	v_or3_b32 v1, v8, v1, v2
	v_add_u32_e32 v136, v1, v9
	v_lshlrev_b32_e32 v1, 4, v12
	s_waitcnt vmcnt(8)
	s_barrier
	s_waitcnt vmcnt(6)
	s_cmpk_lt_u32 s5, 0x100
	v_and_b32_e32 v1, 0x78000, v1
	s_cselect_b64 s[18:19], -1, 0
	v_or3_b32 v1, v8, v1, v2
	s_add_i32 s46, 0, 0x10000
	s_add_i32 s47, 0, 0x14000
	s_ashr_i32 s43, s42, 31
	v_or_b32_e32 v150, s22, v11
	v_mov_b32_e32 v137, v131
	v_add_u32_e32 v138, v1, v9
	v_mov_b32_e32 v139, v131
	v_mov_b64_e32 v[140:141], 0x100
	v_mov_b64_e32 v[142:143], 0xff
	v_add_u32_e32 v151, s46, v149
	v_add_u32_e32 v152, s47, v149
	v_add_u32_e32 v153, 0, v0
	s_barrier
	s_branch .LBB0_596

; #define PG8_STAGE(bufoff, gbase, voff) do { _Pragma("unroll") for (int _i = 0; _i < 2; ++_i) \
;         __builtin_amdgcn_global_load_lds((const unsigned*)((const char*)(gbase) + (voff)[_i]), (PG8_LAS unsigned*)(lds + (bufoff) + ldsw + _i * 8192), 16, 0, 0); } while (0)
; #define PG8_WAIT_V(n) asm volatile("s_waitcnt vmcnt(" #n ")" ::: "memory")
; #define PG8_BAR __builtin_amdgcn_s_barrier()
; template <class Epi, class Sched, bool ALIGN_EPI = false, bool SP2 = false>
; __device__ __forceinline__ void gemm_phase(PG8_LAS unsigned char* lds, const Gemm g, const Sched& S, const Epi& E) {
;     ...
;         PG8_STAGE(PG8_SB(0, 0), cB, voffB); PG8_STAGE(PG8_SB(0, 1), cB + hstep, voffB); PG8_STAGE(PG8_SA(0, 0), cA, voffA); PG8_STAGE(PG8_SA(0, 1), cA + hstep, voffA);
;         if (wr == 1) PG8_BAR;
;         PG8_WAIT_V(2); PG8_BAR;
;         PG8_STAGE(PG8_SB(1, 0), cB + kstep, voffB); PG8_STAGE(PG8_SA(1, 0), cA + kstep, voffA); PG8_STAGE(PG8_SB(1, 1), cB + hstep + kstep, voffB);
;         PG8_WAIT_V(6); PG8_BAR;
.LBB0_703:
	s_lshl_b32 s6, s6, 5
	s_and_b32 s18, s6, 0x60
	s_mov_b64 s[6:7], 0x80
	s_add_i32 m0, s11, 0x18000
	v_lshl_add_u64 v[6:7], v[6:7], 0, s[6:7]
	s_ashr_i32 s36, s42, 31
	s_lshl_b32 s15, s14, 13
	s_lshl_b32 s19, s18, 7
	global_load_lds_dwordx4 v[6:7], off
	v_lshl_add_u64 v[4:5], v[4:5], 0, s[6:7]
	s_add_i32 m0, s11, 0x1a000
	s_add_i32 s37, s11, 0x8000
	s_add_i32 s38, s11, 0xa000
	global_load_lds_dwordx4 v[4:5], off
	v_lshl_add_u64 v[0:1], v[0:1], 0, s[6:7]
	s_mov_b32 m0, s37
	s_add_u32 s16, s28, 0x40080
	global_load_lds_dwordx4 v[0:1], off
	v_lshl_add_u64 v[0:1], v[2:3], 0, s[6:7]
	s_mov_b32 m0, s38
	s_addc_u32 s17, s29, 0
	global_load_lds_dwordx4 v[0:1], off
	s_add_i32 m0, s11, 0x1c000
	v_lshl_add_u64 v[0:1], s[16:17], 0, v[130:131]
	global_load_lds_dwordx4 v[0:1], off
	v_lshl_add_u64 v[0:1], s[16:17], 0, v[134:135]
	s_add_i32 m0, s11, 0x1e000
	s_sext_i32_i8 s41, s4
	global_load_lds_dwordx4 v[0:1], off
	v_lshlrev_b32_e32 v0, 1, v9
	v_lshlrev_b32_e32 v1, 6, v162
	s_movk_i32 s4, 0x3c0
	v_lshlrev_b32_e32 v2, 2, v162
	v_and_or_b32 v1, v1, s4, v0
	v_and_b32_e32 v2, 32, v2
	v_bitop3_b32 v155, s19, v1, v2 bitop3:0xf6
	v_lshlrev_b32_e32 v1, 8, v162
	v_and_b32_e32 v1, 0x38000, v1
	v_lshlrev_b32_e32 v2, 11, v8
	v_or3_b32 v1, v11, v1, v2
	v_lshlrev_b32_e32 v3, 2, v152
	v_add_u32_e32 v136, v1, v154
	v_lshlrev_b32_e32 v1, 4, v10
	v_lshl_or_b32 v0, v152, 6, v0
	v_and_b32_e32 v3, 32, v3
	s_waitcnt vmcnt(8)
	s_barrier
	s_waitcnt vmcnt(6)
	s_cmpk_lt_u32 s5, 0x100
	v_and_b32_e32 v1, 0x78000, v1
	v_lshl_or_b32 v153, s14, 6, v152
	v_bitop3_b32 v0, v0, s15, v3 bitop3:0xde
	s_cselect_b64 s[14:15], -1, 0
	v_or3_b32 v1, v11, v1, v2
	s_add_i32 s39, 0, 0x10000
	s_add_i32 s40, 0, 0x14000
	v_or_b32_e32 v156, s18, v9
	v_mov_b32_e32 v137, v131
	v_add_u32_e32 v138, v1, v154
	v_mov_b32_e32 v139, v131
	v_mov_b64_e32 v[140:141], 0x100
	v_mov_b64_e32 v[142:143], 0xff
	v_add_u32_e32 v157, s39, v155
	v_add_u32_e32 v158, s40, v155
	v_add_u32_e32 v159, 0, v0
	s_barrier
	s_branch .LBB0_706

; #define PG8_STAGE(bufoff, gbase, voff) do { _Pragma("unroll") for (int _i = 0; _i < 2; ++_i) \
;         __builtin_amdgcn_global_load_lds((const unsigned*)((const char*)(gbase) + (voff)[_i]), (PG8_LAS unsigned*)(lds + (bufoff) + ldsw + _i * 8192), 16, 0, 0); } while (0)
; #define PG8_WAIT_V(n) asm volatile("s_waitcnt vmcnt(" #n ")" ::: "memory")
; #define PG8_BAR __builtin_amdgcn_s_barrier()
; template <class Epi, class Sched, bool ALIGN_EPI = false, bool SP2 = false>
; __device__ __forceinline__ void gemm_phase(PG8_LAS unsigned char* lds, const Gemm g, const Sched& S, const Epi& E) {
;     ...
;         PG8_STAGE(PG8_SB(0, 0), cB, voffB); PG8_STAGE(PG8_SB(0, 1), cB + hstep, voffB); PG8_STAGE(PG8_SA(0, 0), cA, voffA); PG8_STAGE(PG8_SA(0, 1), cA + hstep, voffA);
;         if (wr == 1) PG8_BAR;
;         PG8_WAIT_V(2); PG8_BAR;
;         PG8_STAGE(PG8_SB(1, 0), cB + kstep, voffB); PG8_STAGE(PG8_SA(1, 0), cA + kstep, voffA); PG8_STAGE(PG8_SB(1, 1), cB + hstep + kstep, voffB);
;         PG8_WAIT_V(6); PG8_BAR;
.LBB0_793:
	s_mov_b64 s[16:17], 0x80
	s_and_b32 s46, s0, 3
	s_add_i32 m0, s10, 0x18000
	v_lshl_add_u64 v[6:7], v[6:7], 0, s[16:17]
	s_ashr_i32 s41, s42, 31
	s_ashr_i32 s43, s2, 31
	s_lshl_b32 s18, s5, 13
	s_lshl_b32 s19, s46, 12
	global_load_lds_dwordx4 v[6:7], off
	v_lshl_add_u64 v[4:5], v[4:5], 0, s[16:17]
	s_add_i32 m0, s10, 0x1a000
	s_add_i32 s47, s10, 0x8000
	s_add_i32 s48, s10, 0xa000
	global_load_lds_dwordx4 v[4:5], off
	v_lshl_add_u64 v[0:1], v[0:1], 0, s[16:17]
	s_mov_b32 m0, s47
	s_add_u32 s0, s36, 0x40080
	global_load_lds_dwordx4 v[0:1], off
	v_lshl_add_u64 v[0:1], v[2:3], 0, s[16:17]
	s_mov_b32 m0, s48
	s_addc_u32 s1, s37, 0
	global_load_lds_dwordx4 v[0:1], off
	s_add_i32 m0, s10, 0x1c000
	v_lshl_add_u64 v[0:1], s[0:1], 0, v[130:131]
	global_load_lds_dwordx4 v[0:1], off
	v_lshl_add_u64 v[0:1], s[0:1], 0, v[134:135]
	s_add_i32 m0, s10, 0x1e000
	v_lshlrev_b32_e32 v3, 6, v162
	global_load_lds_dwordx4 v[0:1], off
	v_bfe_u32 v0, v162, 4, 2
	v_lshlrev_b32_e32 v2, 4, v0
	s_movk_i32 s0, 0x3c0
	v_lshlrev_b32_e32 v1, 3, v0
	v_and_or_b32 v3, v3, s0, v2
	v_cmp_eq_u32_e64 s[0:1], 0, v0
	v_lshl_or_b32 v0, v148, 6, v2
	v_lshlrev_b32_e32 v2, 2, v148
	v_and_b32_e32 v2, 32, v2
	v_lshl_or_b32 v151, s46, 5, v1
	v_lshlrev_b32_e32 v1, 8, v162
	v_bitop3_b32 v0, v0, s18, v2 bitop3:0xde
	v_and_b32_e32 v1, 0x38000, v1
	v_lshlrev_b32_e32 v2, 11, v8
	v_or3_b32 v1, v10, v1, v2
	v_lshlrev_b32_e32 v4, 2, v162
	v_add_u32_e32 v136, v1, v154
	v_lshlrev_b32_e32 v1, 4, v9
	v_and_b32_e32 v4, 32, v4
	s_waitcnt vmcnt(8)
	s_barrier
	s_waitcnt vmcnt(6)
	s_cmpk_lt_u32 s4, 0x100
	v_and_b32_e32 v1, 0x78000, v1
	v_bitop3_b32 v150, s19, v3, v4 bitop3:0xf6
	s_cselect_b64 s[18:19], -1, 0
	v_or3_b32 v1, v10, v1, v2
	s_add_i32 s49, 0, 0x10000
	s_add_i32 s50, 0, 0x14000
	v_add_u32_e32 v155, 0, v0
	v_mbcnt_lo_u32_b32 v0, -1, 0
	v_lshl_or_b32 v149, s5, 6, v148
	v_mov_b32_e32 v137, v131
	v_add_u32_e32 v138, v1, v154
	v_mov_b32_e32 v139, v131
	v_mov_b64_e32 v[140:141], 0x100
	v_mov_b64_e32 v[142:143], 0xff
	v_add_u32_e32 v152, s49, v150
	v_add_u32_e32 v153, s50, v150
	v_mbcnt_hi_u32_b32 v156, -1, v0
	s_mov_b32 s51, 0x58000
	s_barrier
	s_branch .LBB0_796

; #define PG8_STAGE(bufoff, gbase, voff) do { _Pragma("unroll") for (int _i = 0; _i < 2; ++_i) \
;         __builtin_amdgcn_global_load_lds((const unsigned*)((const char*)(gbase) + (voff)[_i]), (PG8_LAS unsigned*)(lds + (bufoff) + ldsw + _i * 8192), 16, 0, 0); } while (0)
; #define PG8_WAIT_V(n) asm volatile("s_waitcnt vmcnt(" #n ")" ::: "memory")
; #define PG8_BAR __builtin_amdgcn_s_barrier()
; template <class Epi, class Sched, bool ALIGN_EPI = false, bool SP2 = false>
; __device__ __forceinline__ void gemm_phase(PG8_LAS unsigned char* lds, const Gemm g, const Sched& S, const Epi& E) {
;     ...
;         PG8_STAGE(PG8_SB(0, 0), cB, voffB); PG8_STAGE(PG8_SB(0, 1), cB + hstep, voffB); PG8_STAGE(PG8_SA(0, 0), cA, voffA); PG8_STAGE(PG8_SA(0, 1), cA + hstep, voffA);
;         if (wr == 1) PG8_BAR;
;         PG8_WAIT_V(2); PG8_BAR;
;         PG8_STAGE(PG8_SB(1, 0), cB + kstep, voffB); PG8_STAGE(PG8_SA(1, 0), cA + kstep, voffA); PG8_STAGE(PG8_SB(1, 1), cB + hstep + kstep, voffB);
;         PG8_WAIT_V(6); PG8_BAR;
.LBB0_969:
	s_lshl_b32 s8, s8, 5
	s_and_b32 s20, s8, 0x60
	s_mov_b64 s[8:9], 0x80
	s_add_i32 m0, s27, 0x18000
	v_lshl_add_u64 v[6:7], v[6:7], 0, s[8:9]
	s_ashr_i32 s41, s42, 31
	s_lshl_b32 s11, s10, 13
	global_load_lds_dwordx4 v[6:7], off
	v_lshl_add_u64 v[4:5], v[4:5], 0, s[8:9]
	s_add_i32 m0, s27, 0x1a000
	s_add_i32 s43, s27, 0x8000
	s_add_i32 s46, s27, 0xa000
	global_load_lds_dwordx4 v[4:5], off
	v_lshl_add_u64 v[0:1], v[0:1], 0, s[8:9]
	s_mov_b32 m0, s43
	s_add_u32 s18, s30, 0x40080
	global_load_lds_dwordx4 v[0:1], off
	v_lshl_add_u64 v[0:1], v[2:3], 0, s[8:9]
	s_mov_b32 m0, s46
	s_addc_u32 s19, s31, 0
	global_load_lds_dwordx4 v[0:1], off
	s_add_i32 m0, s27, 0x1c000
	v_lshl_add_u64 v[0:1], s[18:19], 0, v[130:131]
	global_load_lds_dwordx4 v[0:1], off
	v_lshl_add_u64 v[0:1], s[18:19], 0, v[134:135]
	s_add_i32 m0, s27, 0x1e000
	v_lshlrev_b32_e32 v2, 11, v9
	global_load_lds_dwordx4 v[0:1], off
	v_lshlrev_b32_e32 v1, 2, v145
	v_lshl_or_b32 v0, v145, 6, v146
	v_and_b32_e32 v1, 32, v1
	v_bitop3_b32 v0, v0, s11, v1 bitop3:0xde
	v_lshlrev_b32_e32 v1, 8, v162
	v_and_b32_e32 v1, 0x38000, v1
	v_or3_b32 v1, v8, v1, v2
	v_add_u32_e32 v136, v1, v154
	v_lshlrev_b32_e32 v1, 4, v10
	s_waitcnt vmcnt(8)
	s_barrier
	s_waitcnt vmcnt(6)
	s_cmpk_lt_u32 s1, 0x100
	v_and_b32_e32 v1, 0x78000, v1
	v_lshl_or_b32 v153, s10, 6, v145
	v_lshl_or_b32 v155, s20, 7, v147
	s_cselect_b64 s[10:11], -1, 0
	v_or3_b32 v1, v8, v1, v2
	s_add_i32 s47, 0, 0x10000
	s_add_i32 s48, 0, 0x14000
	s_sext_i32_i16 s50, s0
	v_or_b32_e32 v156, s20, v144
	v_mov_b32_e32 v137, v131
	v_add_u32_e32 v138, v1, v154
	v_mov_b32_e32 v139, v131
	v_mov_b64_e32 v[140:141], 0x580
	v_mov_b64_e32 v[142:143], 0x57f
	v_add_u32_e32 v157, s47, v155
	v_add_u32_e32 v158, s48, v155
	v_add_u32_e32 v159, 0, v0
	s_movk_i32 s49, 0x1600
	s_barrier
	s_branch .LBB0_972

; #define PG8_STAGE(bufoff, gbase, voff) do { _Pragma("unroll") for (int _i = 0; _i < 2; ++_i) \
;         __builtin_amdgcn_global_load_lds((const unsigned*)((const char*)(gbase) + (voff)[_i]), (PG8_LAS unsigned*)(lds + (bufoff) + ldsw + _i * 8192), 16, 0, 0); } while (0)
; #define PG8_WAIT_V(n) asm volatile("s_waitcnt vmcnt(" #n ")" ::: "memory")
; #define PG8_BAR __builtin_amdgcn_s_barrier()
; template <class Epi, class Sched, bool ALIGN_EPI = false, bool SP2 = false>
; __device__ __forceinline__ void gemm_phase(PG8_LAS unsigned char* lds, const Gemm g, const Sched& S, const Epi& E) {
;     ...
;         PG8_STAGE(PG8_SB(0, 0), cB, voffB); PG8_STAGE(PG8_SB(0, 1), cB + hstep, voffB); PG8_STAGE(PG8_SA(0, 0), cA, voffA); PG8_STAGE(PG8_SA(0, 1), cA + hstep, voffA);
;         if (wr == 1) PG8_BAR;
;         PG8_WAIT_V(2); PG8_BAR;
;         PG8_STAGE(PG8_SB(1, 0), cB + kstep, voffB); PG8_STAGE(PG8_SA(1, 0), cA + kstep, voffA); PG8_STAGE(PG8_SB(1, 1), cB + hstep + kstep, voffB);
;         PG8_WAIT_V(6); PG8_BAR;
.LBB0_994:
	s_lshl_b32 s9, s9, 5
	s_lshl_b32 s19, s18, 13
	s_and_b32 s20, s9, 0x60
	s_and_b64 s[0:1], s[0:1], exec
	s_cselect_b32 s58, s8, 1
	s_mov_b64 s[8:9], 0x80
	s_add_i32 m0, s23, 0x18000
	v_lshl_add_u64 v[6:7], v[6:7], 0, s[8:9]
	s_ashr_i32 s59, s58, 31
	global_load_lds_dwordx4 v[6:7], off
	v_lshl_add_u64 v[4:5], v[4:5], 0, s[8:9]
	s_add_i32 m0, s23, 0x1a000
	s_add_i32 s60, s23, 0x8000
	s_add_i32 s61, s23, 0xa000
	global_load_lds_dwordx4 v[4:5], off
	v_lshl_add_u64 v[0:1], v[0:1], 0, s[8:9]
	s_mov_b32 m0, s60
	s_add_u32 s0, s24, 0x10080
	global_load_lds_dwordx4 v[0:1], off
	v_lshl_add_u64 v[0:1], v[2:3], 0, s[8:9]
	s_mov_b32 m0, s61
	s_addc_u32 s1, s25, 0
	global_load_lds_dwordx4 v[0:1], off
	s_add_i32 m0, s23, 0x1c000
	v_lshl_add_u64 v[0:1], s[0:1], 0, v[130:131]
	global_load_lds_dwordx4 v[0:1], off
	v_lshl_add_u64 v[0:1], s[0:1], 0, v[134:135]
	s_add_i32 m0, s23, 0x1e000
	s_cmpk_lt_u32 s11, 0x100
	global_load_lds_dwordx4 v[0:1], off
	v_lshlrev_b32_e32 v1, 2, v145
	v_lshl_or_b32 v0, v145, 6, v146
	v_and_b32_e32 v1, 32, v1
	s_waitcnt vmcnt(8)
	s_barrier
	s_waitcnt vmcnt(6)
	s_sext_i32_i8 s64, s10
	v_bitop3_b32 v0, v0, s19, v1 bitop3:0xde
	v_lshl_or_b32 v141, s20, 7, v147
	s_cselect_b64 s[10:11], -1, 0
	s_add_i32 s62, 0, 0x10000
	s_add_i32 s63, 0, 0x14000
	v_lshl_or_b32 v140, s18, 6, v145
	v_or_b32_e32 v142, s20, v144
	v_mov_b64_e32 v[136:137], 0x100
	v_mov_b64_e32 v[138:139], 0xff
	v_add_u32_e32 v143, s62, v141
	v_add_u32_e32 v144, s63, v141
	v_add_u32_e32 v145, 0, v0
	s_barrier
	s_branch .LBB0_997

; #define PG8_STAGE(bufoff, gbase, voff) do { _Pragma("unroll") for (int _i = 0; _i < 2; ++_i) \
;         __builtin_amdgcn_global_load_lds((const unsigned*)((const char*)(gbase) + (voff)[_i]), (PG8_LAS unsigned*)(lds + (bufoff) + ldsw + _i * 8192), 16, 0, 0); } while (0)
; #define PG8_WAIT_V(n) asm volatile("s_waitcnt vmcnt(" #n ")" ::: "memory")
; #define PG8_BAR __builtin_amdgcn_s_barrier()
; template <class Epi, class Sched, bool ALIGN_EPI = false, bool SP2 = false>
; __device__ __forceinline__ void gemm_phase(PG8_LAS unsigned char* lds, const Gemm g, const Sched& S, const Epi& E) {
;     ...
;         PG8_STAGE(PG8_SB(0, 0), cB, voffB); PG8_STAGE(PG8_SB(0, 1), cB + hstep, voffB); PG8_STAGE(PG8_SA(0, 0), cA, voffA); PG8_STAGE(PG8_SA(0, 1), cA + hstep, voffA);
;         if (wr == 1) PG8_BAR;
;         PG8_WAIT_V(2); PG8_BAR;
;         PG8_STAGE(PG8_SB(1, 0), cB + kstep, voffB); PG8_STAGE(PG8_SA(1, 0), cA + kstep, voffA); PG8_STAGE(PG8_SB(1, 1), cB + hstep + kstep, voffB);
;         PG8_WAIT_V(6); PG8_BAR;
.LBB0_1071:
	s_mov_b64 s[10:11], 0x80
	s_and_b32 s49, s0, 3
	s_add_i32 m0, s33, 0x18000
	v_lshl_add_u64 v[6:7], v[6:7], 0, s[10:11]
	s_ashr_i32 s47, s42, 31
	s_ashr_i32 s48, s2, 31
	s_lshl_b32 s6, s5, 13
	s_lshl_b32 s7, s49, 12
	global_load_lds_dwordx4 v[6:7], off
	v_lshl_add_u64 v[4:5], v[4:5], 0, s[10:11]
	s_add_i32 m0, s33, 0x1a000
	s_add_i32 s50, s33, 0x8000
	s_add_i32 s51, s33, 0xa000
	global_load_lds_dwordx4 v[4:5], off
	v_lshl_add_u64 v[0:1], v[0:1], 0, s[10:11]
	s_mov_b32 m0, s50
	s_add_u32 s0, s36, 0xb0080
	global_load_lds_dwordx4 v[0:1], off
	v_lshl_add_u64 v[0:1], v[2:3], 0, s[10:11]
	s_mov_b32 m0, s51
	s_addc_u32 s1, s37, 0
	global_load_lds_dwordx4 v[0:1], off
	s_add_i32 m0, s33, 0x1c000
	v_lshl_add_u64 v[0:1], s[0:1], 0, v[130:131]
	global_load_lds_dwordx4 v[0:1], off
	v_lshl_add_u64 v[0:1], s[0:1], 0, v[134:135]
	s_add_i32 m0, s33, 0x1e000
	v_lshlrev_b32_e32 v3, 6, v162
	global_load_lds_dwordx4 v[0:1], off
	v_bfe_u32 v0, v162, 4, 2
	v_lshlrev_b32_e32 v2, 4, v0
	s_movk_i32 s0, 0x3c0
	v_lshlrev_b32_e32 v1, 3, v0
	v_and_or_b32 v3, v3, s0, v2
	v_cmp_eq_u32_e64 s[0:1], 0, v0
	v_lshl_or_b32 v0, v148, 6, v2
	v_lshlrev_b32_e32 v2, 2, v148
	v_lshlrev_b32_e32 v4, 2, v162
	v_and_b32_e32 v2, 32, v2
	v_and_b32_e32 v4, 32, v4
	v_bitop3_b32 v0, v0, s6, v2 bitop3:0xde
	s_waitcnt vmcnt(8)
	s_barrier
	s_waitcnt vmcnt(6)
	v_lshl_or_b32 v151, s49, 5, v1
	s_cmpk_lt_u32 s4, 0x100
	v_add_u16_e32 v1, v10, v154
	v_bitop3_b32 v150, s7, v3, v4 bitop3:0xf6
	s_cselect_b64 s[20:21], -1, 0
	v_lshrrev_b16_e32 v1, 1, v1
	s_add_i32 s52, 0, 0x10000
	s_add_i32 s53, 0, 0x14000
	v_add_u32_e32 v155, 0, v0
	v_mbcnt_lo_u32_b32 v0, -1, 0
	v_lshl_or_b32 v149, s5, 6, v148
	v_add_lshl_u32 v136, v8, v1, 1
	v_mov_b32_e32 v137, v131
	v_add_lshl_u32 v138, v9, v1, 1
	v_mov_b32_e32 v139, v131
	v_mov_b64_e32 v[140:141], 0x100
	v_mov_b64_e32 v[142:143], 0xff
	v_add_u32_e32 v152, s52, v150
	v_add_u32_e32 v153, s53, v150
	v_mbcnt_hi_u32_b32 v156, -1, v0
	s_mov_b64 s[22:23], 0x40000
	s_mov_b32 s54, 0x40000
	s_mov_b64 s[24:25], 0x48000
	s_mov_b32 s55, 0x48000
	s_mov_b64 s[26:27], 0x50000
	s_mov_b32 s58, 0x50000
	s_mov_b64 s[28:29], 0x58000
	s_mov_b32 s59, 0x58000
	s_barrier
	s_branch .LBB0_1074

; #define PG8_STAGE(bufoff, gbase, voff) do { _Pragma("unroll") for (int _i = 0; _i < 2; ++_i) \
;         __builtin_amdgcn_global_load_lds((const unsigned*)((const char*)(gbase) + (voff)[_i]), (PG8_LAS unsigned*)(lds + (bufoff) + ldsw + _i * 8192), 16, 0, 0); } while (0)
; #define PG8_WAIT_V(n) asm volatile("s_waitcnt vmcnt(" #n ")" ::: "memory")
; #define PG8_BAR __builtin_amdgcn_s_barrier()
; template <class Epi, class Sched, bool ALIGN_EPI = false, bool SP2 = false>
; __device__ __forceinline__ void gemm_phase(PG8_LAS unsigned char* lds, const Gemm g, const Sched& S, const Epi& E) {
;     ...
;         PG8_STAGE(PG8_SB(0, 0), cB, voffB); PG8_STAGE(PG8_SB(0, 1), cB + hstep, voffB); PG8_STAGE(PG8_SA(0, 0), cA, voffA); PG8_STAGE(PG8_SA(0, 1), cA + hstep, voffA);
;         if (wr == 1) PG8_BAR;
;         PG8_WAIT_V(2); PG8_BAR;
;         PG8_STAGE(PG8_SB(1, 0), cB + kstep, voffB); PG8_STAGE(PG8_SA(1, 0), cA + kstep, voffA); PG8_STAGE(PG8_SB(1, 1), cB + hstep + kstep, voffB);
;         PG8_WAIT_V(6); PG8_BAR;
.LBB0_1253:
	s_mov_b64 s[16:17], 0x80
	s_and_b32 s54, s4, 3
	s_add_i32 m0, s33, 0x18000
	v_lshl_add_u64 v[6:7], v[6:7], 0, s[16:17]
	s_ashr_i32 s52, s42, 31
	s_ashr_i32 s53, s2, 31
	s_lshl_b32 s18, s7, 13
	s_lshl_b32 s19, s54, 12
	global_load_lds_dwordx4 v[6:7], off
	v_lshl_add_u64 v[4:5], v[4:5], 0, s[16:17]
	s_add_i32 m0, s33, 0x1a000
	s_add_i32 s55, s33, 0x8000
	s_add_i32 s58, s33, 0xa000
	global_load_lds_dwordx4 v[4:5], off
	v_lshl_add_u64 v[0:1], v[0:1], 0, s[16:17]
	s_mov_b32 m0, s55
	s_add_u32 s4, s46, 0x40080
	global_load_lds_dwordx4 v[0:1], off
	v_lshl_add_u64 v[0:1], v[2:3], 0, s[16:17]
	s_mov_b32 m0, s58
	s_addc_u32 s5, s47, 0
	global_load_lds_dwordx4 v[0:1], off
	s_add_i32 m0, s33, 0x1c000
	v_lshl_add_u64 v[0:1], s[4:5], 0, v[130:131]
	global_load_lds_dwordx4 v[0:1], off
	v_lshl_add_u64 v[0:1], s[4:5], 0, v[134:135]
	s_add_i32 m0, s33, 0x1e000
	v_lshlrev_b32_e32 v3, 6, v162
	global_load_lds_dwordx4 v[0:1], off
	v_bfe_u32 v0, v162, 4, 2
	v_lshlrev_b32_e32 v2, 4, v0
	s_movk_i32 s4, 0x3c0
	v_lshlrev_b32_e32 v1, 3, v0
	v_and_or_b32 v3, v3, s4, v2
	v_cmp_eq_u32_e64 s[4:5], 0, v0
	v_lshl_or_b32 v0, v150, 6, v2
	v_lshlrev_b32_e32 v2, 2, v150
	v_and_b32_e32 v2, 32, v2
	v_lshl_or_b32 v153, s54, 5, v1
	v_lshlrev_b32_e32 v1, 8, v162
	v_bitop3_b32 v0, v0, s18, v2 bitop3:0xde
	v_and_b32_e32 v1, 0x38000, v1
	v_lshlrev_b32_e32 v2, 11, v8
	v_or3_b32 v1, v10, v1, v2
	v_lshlrev_b32_e32 v4, 2, v162
	v_add_u32_e32 v136, v1, v154
	v_lshlrev_b32_e32 v1, 4, v9
	v_and_b32_e32 v4, 32, v4
	s_waitcnt vmcnt(8)
	s_barrier
	s_waitcnt vmcnt(6)
	s_cmpk_lt_u32 s6, 0x100
	v_and_b32_e32 v1, 0x78000, v1
	v_bitop3_b32 v152, s19, v3, v4 bitop3:0xf6
	s_cselect_b64 s[18:19], -1, 0
	v_or3_b32 v1, v10, v1, v2
	s_add_i32 s59, 0, 0x10000
	s_add_i32 s60, 0, 0x14000
	v_add_u32_e32 v157, 0, v0
	v_mbcnt_lo_u32_b32 v0, -1, 0
	v_lshl_or_b32 v151, s7, 6, v150
	v_mov_b32_e32 v137, v131
	v_add_u32_e32 v138, v1, v154
	v_mov_b32_e32 v139, v131
	v_mov_b64_e32 v[140:141], 0x100
	v_mov_b64_e32 v[142:143], 0xff
	v_add_u32_e32 v155, s59, v152
	v_add_u32_e32 v156, s60, v152
	v_mbcnt_hi_u32_b32 v158, -1, v0
	s_mov_b64 s[20:21], 0x48000
	s_mov_b64 s[22:23], 0x50000
	s_mov_b64 s[24:25], 0x58000
	s_barrier
	s_branch .LBB0_1256
